# scan1 step loop: nt cache hint on the 12 streaming row loads (gate arrays and conv output are read once in this phase)
# baseline (speedup 1.0000x reference)
; __device__ __forceinline__ float sigmoidf_(float x) { return __builtin_amdgcn_rcpf(1.0f + __expf(-x)); }
; __device__ __forceinline__ void rg_unpack8(const u32x4 w, float* v) { v[0] = bflo(w.x); v[1] = bfhi(w.x); v[2] = bflo(w.y); v[3] = bfhi(w.y); v[4] = bflo(w.z); v[5] = bfhi(w.z); v[6] = bflo(w.w); v[7] = bfhi(w.w); }
; __device__ __forceinline__ void rg_ab(float ra, float ri, float x, float ba, float bx, float sp, float& a, float& b) {
;     const float r = sigmoidf_(ra + ba), ig = sigmoidf_(ri + bx); const float l2 = r * sp; a = exp2f(l2);
;     const float x2 = 1.3862943611198906f * l2;
;     const float om = x2 > -0.125f ? -x2 * (1.0f + x2 * (0.5f + x2 * (0.16666667f + x2 * (0.041666668f + x2 * 0.0083333338f)))) : 1.0f - __expf(x2);
; __device__ __forceinline__ void rg_scan1_phase(const bf16_t* RA0, const bf16_t* RI0, const bf16_t* RA1, const bf16_t* RI1, const bf16_t* XCV, const float* bap, const float* bxp, const float* lamp, float* CAR, int gtid, int ngt) {
;     ...
;         for (int i = 0; i < 32; ++i) { const size_t off = (size_t)(rbase + step * i) * DRNN + 8 * cg;
;             float ra[8], ri[8], xv[8]; rg_unpack8(*(const u32x4*)(RA + off), ra); rg_unpack8(*(const u32x4*)(RI + off), ri); rg_unpack8(*(const u32x4*)(XCV + off), xv);
; #pragma unroll
;             for (int e = 0; e < 8; ++e) { float a, bb; rg_ab(ra[e], ri[e], xv[e], ba[e], bx[e], sp[e], a, bb); p[e] *= a; sv[e] = a * sv[e] + bb; } }
.LBB0_1014:
	s_add_i32 s6, s4, 3
	v_mov_b32_e32 v32, s6
	v_mov_b32_e32 v33, s26
	v_cndmask_b32_e32 v32, v32, v33, vcc
	v_add_u32_e32 v32, v32, v80
	v_mad_i64_i32 v[32:33], s[6:7], v32, s34, v[70:71]
	v_lshlrev_b64 v[32:33], 1, v[32:33]
	v_lshl_add_u64 v[34:35], v[72:73], 0, v[32:33]
	global_load_dwordx4 v[40:43], v[34:35], off nt
	v_lshl_add_u64 v[34:35], v[74:75], 0, v[32:33]
	v_lshl_add_u64 v[32:33], s[20:21], 0, v[32:33]
	global_load_dwordx4 v[36:39], v[34:35], off nt
	s_waitcnt vmcnt(1)
	v_lshlrev_b32_e32 v44, 16, v40
	global_load_dwordx4 v[32:35], v[32:33], off nt
	v_add_f32_e32 v44, v0, v44
	v_mul_f32_e32 v44, 0xbfb8aa3b, v44
	v_exp_f32_e32 v44, v44
	s_nop 0
	v_add_f32_e32 v44, 1.0, v44
	v_rcp_f32_e32 v44, v44
	s_nop 0
	v_mul_f32_e32 v101, v88, v44
	v_mul_f32_e32 v44, 0x3fb17218, v101
	v_mul_f32_e32 v160, 0x3fb8aa3b, v44
	v_exp_f32_e32 v160, v160
	v_fmamk_f32 v161, v44, 0x3c088889, v202
	v_fmaak_f32 v161, v44, v161, 0x3e2aaaab
	v_fma_f32 v161, v44, v161, 0.5
	v_fma_f32 v161, v44, v161, 1.0
	v_mul_f32_e64 v161, v161, -v44
	v_sub_f32_e32 v160, 1.0, v160
	v_cmp_nlt_f32_e64 s[6:7], s5, v44
	s_nop 1
	v_cndmask_b32_e64 v77, v161, v160, s[6:7]
	v_and_b32_e32 v40, 0xffff0000, v40
	v_add_f32_e32 v40, v1, v40
	v_mul_f32_e32 v40, 0xbfb8aa3b, v40
	v_exp_f32_e32 v40, v40
	s_nop 0
	v_add_f32_e32 v40, 1.0, v40
	v_rcp_f32_e32 v40, v40
	s_nop 0
	v_mul_f32_e32 v102, v87, v40
	v_mul_f32_e32 v40, 0x3fb17218, v102
	v_mul_f32_e32 v160, 0x3fb8aa3b, v40
	v_exp_f32_e32 v160, v160
	v_fmamk_f32 v161, v40, 0x3c088889, v202
	v_fmaak_f32 v161, v40, v161, 0x3e2aaaab
	v_fma_f32 v161, v40, v161, 0.5
	v_fma_f32 v161, v40, v161, 1.0
	v_mul_f32_e64 v161, v161, -v40
	v_sub_f32_e32 v160, 1.0, v160
	v_cmp_nlt_f32_e64 s[6:7], s5, v40
	s_nop 1
	v_cndmask_b32_e64 v89, v161, v160, s[6:7]
	v_lshlrev_b32_e32 v40, 16, v41
	v_add_f32_e32 v40, v2, v40
	v_mul_f32_e32 v40, 0xbfb8aa3b, v40
	v_exp_f32_e32 v40, v40
	s_nop 0
	v_add_f32_e32 v40, 1.0, v40
	v_rcp_f32_e32 v40, v40
	s_nop 0
	v_mul_f32_e32 v103, v86, v40
	v_mul_f32_e32 v40, 0x3fb17218, v103
	v_mul_f32_e32 v160, 0x3fb8aa3b, v40
	v_exp_f32_e32 v160, v160
	v_fmamk_f32 v161, v40, 0x3c088889, v202
	v_fmaak_f32 v161, v40, v161, 0x3e2aaaab
	v_fma_f32 v161, v40, v161, 0.5
	v_fma_f32 v161, v40, v161, 1.0
	v_mul_f32_e64 v161, v161, -v40
	v_sub_f32_e32 v160, 1.0, v160
	v_cmp_nlt_f32_e64 s[6:7], s5, v40
	s_nop 1
	v_cndmask_b32_e64 v91, v161, v160, s[6:7]
	v_and_b32_e32 v40, 0xffff0000, v41
	v_add_f32_e32 v40, v3, v40
	v_mul_f32_e32 v40, 0xbfb8aa3b, v40
	v_exp_f32_e32 v40, v40
	s_nop 0
	v_add_f32_e32 v40, 1.0, v40
	v_rcp_f32_e32 v40, v40
	s_nop 0
	v_mul_f32_e32 v104, v85, v40
	v_mul_f32_e32 v40, 0x3fb17218, v104
	v_mul_f32_e32 v160, 0x3fb8aa3b, v40
	v_exp_f32_e32 v160, v160
	v_fmamk_f32 v161, v40, 0x3c088889, v202
	v_fmaak_f32 v161, v40, v161, 0x3e2aaaab
	v_fma_f32 v161, v40, v161, 0.5
	v_fma_f32 v161, v40, v161, 1.0
	v_mul_f32_e64 v161, v161, -v40
	v_sub_f32_e32 v160, 1.0, v160
	v_cmp_nlt_f32_e64 s[6:7], s5, v40
	s_nop 1
	v_cndmask_b32_e64 v93, v161, v160, s[6:7]
	v_lshlrev_b32_e32 v40, 16, v42
	v_add_f32_e32 v40, v8, v40
	v_mul_f32_e32 v40, 0xbfb8aa3b, v40
	v_exp_f32_e32 v40, v40
	s_nop 0
	v_add_f32_e32 v40, 1.0, v40
	v_rcp_f32_e32 v40, v40
	s_nop 0
	v_mul_f32_e32 v106, v84, v40
	v_mul_f32_e32 v40, 0x3fb17218, v106
	v_mul_f32_e32 v160, 0x3fb8aa3b, v40
	v_exp_f32_e32 v160, v160
	v_fmamk_f32 v161, v40, 0x3c088889, v202
	v_fmaak_f32 v161, v40, v161, 0x3e2aaaab
	v_fma_f32 v161, v40, v161, 0.5
	v_fma_f32 v161, v40, v161, 1.0
	v_mul_f32_e64 v161, v161, -v40
	v_sub_f32_e32 v160, 1.0, v160
	v_cmp_nlt_f32_e64 s[6:7], s5, v40
	s_nop 1
	v_cndmask_b32_e64 v95, v161, v160, s[6:7]
	v_and_b32_e32 v40, 0xffff0000, v42
	v_add_f32_e32 v40, v9, v40
	v_mul_f32_e32 v40, 0xbfb8aa3b, v40
	v_exp_f32_e32 v40, v40
	s_nop 0
	v_add_f32_e32 v40, 1.0, v40
	v_rcp_f32_e32 v40, v40
	s_nop 0
	v_mul_f32_e32 v108, v83, v40
	v_mul_f32_e32 v40, 0x3fb17218, v108
	v_mul_f32_e32 v160, 0x3fb8aa3b, v40
	v_exp_f32_e32 v160, v160
	v_fmamk_f32 v161, v40, 0x3c088889, v202
	v_fmaak_f32 v161, v40, v161, 0x3e2aaaab
	v_fma_f32 v161, v40, v161, 0.5
	v_fma_f32 v161, v40, v161, 1.0
	v_mul_f32_e64 v161, v161, -v40
	v_sub_f32_e32 v160, 1.0, v160
	v_cmp_nlt_f32_e64 s[6:7], s5, v40
	s_nop 1
	v_cndmask_b32_e64 v97, v161, v160, s[6:7]
	v_lshlrev_b32_e32 v40, 16, v43
	v_add_f32_e32 v40, v10, v40
	v_mul_f32_e32 v40, 0xbfb8aa3b, v40
	v_exp_f32_e32 v40, v40
	s_nop 0
	v_add_f32_e32 v40, 1.0, v40
	v_rcp_f32_e32 v40, v40
	s_nop 0
	v_mul_f32_e32 v105, v82, v40
	v_mul_f32_e32 v40, 0x3fb17218, v105
	v_mul_f32_e32 v160, 0x3fb8aa3b, v40
	v_exp_f32_e32 v160, v160
	v_fmamk_f32 v161, v40, 0x3c088889, v202
	v_fmaak_f32 v161, v40, v161, 0x3e2aaaab
	v_fma_f32 v161, v40, v161, 0.5
	v_fma_f32 v161, v40, v161, 1.0
	v_mul_f32_e64 v161, v161, -v40
	v_sub_f32_e32 v160, 1.0, v160
	v_cmp_nlt_f32_e64 s[6:7], s5, v40
	s_nop 1
	v_cndmask_b32_e64 v107, v161, v160, s[6:7]
	v_and_b32_e32 v40, 0xffff0000, v43
	v_add_f32_e32 v40, v11, v40
	v_mul_f32_e32 v40, 0xbfb8aa3b, v40
	v_exp_f32_e32 v40, v40
	s_nop 0
	v_add_f32_e32 v40, 1.0, v40
	v_rcp_f32_e32 v40, v40
	s_nop 0
	v_mul_f32_e32 v92, v81, v40
	v_mul_f32_e32 v40, 0x3fb17218, v92
	v_mul_f32_e32 v160, 0x3fb8aa3b, v40
	v_exp_f32_e32 v160, v160
	v_fmamk_f32 v161, v40, 0x3c088889, v202
	v_fmaak_f32 v161, v40, v161, 0x3e2aaaab
	v_fma_f32 v161, v40, v161, 0.5
	v_fma_f32 v161, v40, v161, 1.0
	v_mul_f32_e64 v161, v161, -v40
	v_sub_f32_e32 v160, 1.0, v160
	v_cmp_nlt_f32_e64 s[6:7], s5, v40
	s_nop 1
	v_cndmask_b32_e64 v90, v161, v160, s[6:7]
	s_add_i32 s6, s4, 2
	s_add_i32 s26, s26, 1
	v_mov_b32_e32 v40, s6
	v_mov_b32_e32 v41, s26
	v_cndmask_b32_e32 v40, v40, v41, vcc
	v_add_u32_e32 v40, v40, v80
	v_mad_i64_i32 v[40:41], s[6:7], v40, s34, v[70:71]
	v_lshlrev_b64 v[44:45], 1, v[40:41]
	v_lshl_add_u64 v[40:41], v[72:73], 0, v[44:45]
	global_load_dwordx4 v[48:51], v[40:41], off nt
	v_lshl_add_u64 v[40:41], v[74:75], 0, v[44:45]
	v_lshl_add_u64 v[44:45], s[20:21], 0, v[44:45]
	global_load_dwordx4 v[40:43], v[40:41], off nt
	s_waitcnt vmcnt(1)
; __device__ __forceinline__ float sigmoidf_(float x) { return __builtin_amdgcn_rcpf(1.0f + __expf(-x)); }
; __device__ __forceinline__ void rg_unpack8(const u32x4 w, float* v) { v[0] = bflo(w.x); v[1] = bfhi(w.x); v[2] = bflo(w.y); v[3] = bfhi(w.y); v[4] = bflo(w.z); v[5] = bfhi(w.z); v[6] = bflo(w.w); v[7] = bfhi(w.w); }
; __device__ __forceinline__ void rg_ab(float ra, float ri, float x, float ba, float bx, float sp, float& a, float& b) {
;     const float r = sigmoidf_(ra + ba), ig = sigmoidf_(ri + bx); const float l2 = r * sp; a = exp2f(l2);
;     const float x2 = 1.3862943611198906f * l2;
;     const float om = x2 > -0.125f ? -x2 * (1.0f + x2 * (0.5f + x2 * (0.16666667f + x2 * (0.041666668f + x2 * 0.0083333338f)))) : 1.0f - __expf(x2);
; __device__ __forceinline__ void rg_scan1_phase(const bf16_t* RA0, const bf16_t* RI0, const bf16_t* RA1, const bf16_t* RI1, const bf16_t* XCV, const float* bap, const float* bxp, const float* lamp, float* CAR, int gtid, int ngt) {
;     ...
;         for (int i = 0; i < 32; ++i) { const size_t off = (size_t)(rbase + step * i) * DRNN + 8 * cg;
;             float ra[8], ri[8], xv[8]; rg_unpack8(*(const u32x4*)(RA + off), ra); rg_unpack8(*(const u32x4*)(RI + off), ri); rg_unpack8(*(const u32x4*)(XCV + off), xv);
; #pragma unroll
;             for (int e = 0; e < 8; ++e) { float a, bb; rg_ab(ra[e], ri[e], xv[e], ba[e], bx[e], sp[e], a, bb); p[e] *= a; sv[e] = a * sv[e] + bb; } }
	v_lshlrev_b32_e32 v52, 16, v48
	global_load_dwordx4 v[44:47], v[44:45], off nt
	v_add_f32_e32 v52, v0, v52
	v_mul_f32_e32 v52, 0xbfb8aa3b, v52
	v_exp_f32_e32 v52, v52
	s_nop 0
	v_add_f32_e32 v52, 1.0, v52
	v_rcp_f32_e32 v52, v52
	s_nop 0
	v_mul_f32_e32 v117, v88, v52
	v_mul_f32_e32 v52, 0x3fb17218, v117
	v_mul_f32_e32 v160, 0x3fb8aa3b, v52
	v_exp_f32_e32 v160, v160
	v_fmamk_f32 v161, v52, 0x3c088889, v202
	v_fmaak_f32 v161, v52, v161, 0x3e2aaaab
	v_fma_f32 v161, v52, v161, 0.5
	v_fma_f32 v161, v52, v161, 1.0
	v_mul_f32_e64 v161, v161, -v52
	v_sub_f32_e32 v160, 1.0, v160
	v_cmp_nlt_f32_e64 s[6:7], s5, v52
	s_nop 1
	v_cndmask_b32_e64 v94, v161, v160, s[6:7]
	v_and_b32_e32 v48, 0xffff0000, v48
	v_add_f32_e32 v48, v1, v48
	v_mul_f32_e32 v48, 0xbfb8aa3b, v48
	v_exp_f32_e32 v48, v48
	s_nop 0
	v_add_f32_e32 v48, 1.0, v48
	v_rcp_f32_e32 v48, v48
	s_nop 0
	v_mul_f32_e32 v118, v87, v48
	v_mul_f32_e32 v48, 0x3fb17218, v118
	v_mul_f32_e32 v160, 0x3fb8aa3b, v48
	v_exp_f32_e32 v160, v160
	v_fmamk_f32 v161, v48, 0x3c088889, v202
	v_fmaak_f32 v161, v48, v161, 0x3e2aaaab
	v_fma_f32 v161, v48, v161, 0.5
	v_fma_f32 v161, v48, v161, 1.0
	v_mul_f32_e64 v161, v161, -v48
	v_sub_f32_e32 v160, 1.0, v160
	v_cmp_nlt_f32_e64 s[6:7], s5, v48
	s_nop 1
	v_cndmask_b32_e64 v96, v161, v160, s[6:7]
	v_lshlrev_b32_e32 v48, 16, v49
	v_add_f32_e32 v48, v2, v48
	v_mul_f32_e32 v48, 0xbfb8aa3b, v48
	v_exp_f32_e32 v48, v48
	s_nop 0
	v_add_f32_e32 v48, 1.0, v48
	v_rcp_f32_e32 v48, v48
	s_nop 0
	v_mul_f32_e32 v119, v86, v48
	v_mul_f32_e32 v48, 0x3fb17218, v119
	v_mul_f32_e32 v160, 0x3fb8aa3b, v48
	v_exp_f32_e32 v160, v160
	v_fmamk_f32 v161, v48, 0x3c088889, v202
	v_fmaak_f32 v161, v48, v161, 0x3e2aaaab
	v_fma_f32 v161, v48, v161, 0.5
	v_fma_f32 v161, v48, v161, 1.0
	v_mul_f32_e64 v161, v161, -v48
	v_sub_f32_e32 v160, 1.0, v160
	v_cmp_nlt_f32_e64 s[6:7], s5, v48
	s_nop 1
	v_cndmask_b32_e64 v99, v161, v160, s[6:7]
	v_and_b32_e32 v48, 0xffff0000, v49
	v_add_f32_e32 v48, v3, v48
	v_mul_f32_e32 v48, 0xbfb8aa3b, v48
	v_exp_f32_e32 v48, v48
	s_nop 0
	v_add_f32_e32 v48, 1.0, v48
	v_rcp_f32_e32 v48, v48
	s_nop 0
	v_mul_f32_e32 v122, v85, v48
	v_mul_f32_e32 v48, 0x3fb17218, v122
	v_mul_f32_e32 v160, 0x3fb8aa3b, v48
	v_exp_f32_e32 v160, v160
	v_fmamk_f32 v161, v48, 0x3c088889, v202
	v_fmaak_f32 v161, v48, v161, 0x3e2aaaab
	v_fma_f32 v161, v48, v161, 0.5
	v_fma_f32 v161, v48, v161, 1.0
	v_mul_f32_e64 v161, v161, -v48
	v_sub_f32_e32 v160, 1.0, v160
	v_cmp_nlt_f32_e64 s[6:7], s5, v48
	s_nop 1
	v_cndmask_b32_e64 v109, v161, v160, s[6:7]
	v_lshlrev_b32_e32 v48, 16, v50
	v_add_f32_e32 v48, v8, v48
	v_mul_f32_e32 v48, 0xbfb8aa3b, v48
	v_exp_f32_e32 v48, v48
	s_nop 0
	v_add_f32_e32 v48, 1.0, v48
	v_rcp_f32_e32 v48, v48
	s_nop 0
	v_mul_f32_e32 v123, v84, v48
	v_mul_f32_e32 v48, 0x3fb17218, v123
	v_mul_f32_e32 v160, 0x3fb8aa3b, v48
	v_exp_f32_e32 v160, v160
	v_fmamk_f32 v161, v48, 0x3c088889, v202
	v_fmaak_f32 v161, v48, v161, 0x3e2aaaab
	v_fma_f32 v161, v48, v161, 0.5
	v_fma_f32 v161, v48, v161, 1.0
	v_mul_f32_e64 v161, v161, -v48
	v_sub_f32_e32 v160, 1.0, v160
	v_cmp_nlt_f32_e64 s[6:7], s5, v48
	s_nop 1
	v_cndmask_b32_e64 v111, v161, v160, s[6:7]
	v_and_b32_e32 v48, 0xffff0000, v50
	v_add_f32_e32 v48, v9, v48
	v_mul_f32_e32 v48, 0xbfb8aa3b, v48
	v_exp_f32_e32 v48, v48
	s_nop 0
	v_add_f32_e32 v48, 1.0, v48
	v_rcp_f32_e32 v48, v48
	s_nop 0
	v_mul_f32_e32 v124, v83, v48
	v_mul_f32_e32 v48, 0x3fb17218, v124
	v_mul_f32_e32 v160, 0x3fb8aa3b, v48
	v_exp_f32_e32 v160, v160
	v_fmamk_f32 v161, v48, 0x3c088889, v202
	v_fmaak_f32 v161, v48, v161, 0x3e2aaaab
	v_fma_f32 v161, v48, v161, 0.5
	v_fma_f32 v161, v48, v161, 1.0
	v_mul_f32_e64 v161, v161, -v48
	v_sub_f32_e32 v160, 1.0, v160
	v_cmp_nlt_f32_e64 s[6:7], s5, v48
	s_nop 1
	v_cndmask_b32_e64 v113, v161, v160, s[6:7]
	v_lshlrev_b32_e32 v48, 16, v51
	v_add_f32_e32 v48, v10, v48
	v_mul_f32_e32 v48, 0xbfb8aa3b, v48
	v_exp_f32_e32 v48, v48
	s_nop 0
	v_add_f32_e32 v48, 1.0, v48
	v_rcp_f32_e32 v48, v48
	s_nop 0
	v_mul_f32_e32 v125, v82, v48
	v_mul_f32_e32 v48, 0x3fb17218, v125
	v_mul_f32_e32 v160, 0x3fb8aa3b, v48
	v_exp_f32_e32 v160, v160
	v_fmamk_f32 v161, v48, 0x3c088889, v202
	v_fmaak_f32 v161, v48, v161, 0x3e2aaaab
	v_fma_f32 v161, v48, v161, 0.5
	v_fma_f32 v161, v48, v161, 1.0
	v_mul_f32_e64 v161, v161, -v48
	v_sub_f32_e32 v160, 1.0, v160
	v_cmp_nlt_f32_e64 s[6:7], s5, v48
	s_nop 1
	v_cndmask_b32_e64 v120, v161, v160, s[6:7]
	v_and_b32_e32 v48, 0xffff0000, v51
	v_add_f32_e32 v48, v11, v48
	v_mul_f32_e32 v48, 0xbfb8aa3b, v48
	v_exp_f32_e32 v48, v48
	s_nop 0
	v_add_f32_e32 v48, 1.0, v48
	v_rcp_f32_e32 v48, v48
	s_nop 0
	v_mul_f32_e32 v100, v81, v48
	v_mul_f32_e32 v48, 0x3fb17218, v100
	v_mul_f32_e32 v160, 0x3fb8aa3b, v48
	v_exp_f32_e32 v160, v160
	v_fmamk_f32 v161, v48, 0x3c088889, v202
	v_fmaak_f32 v161, v48, v161, 0x3e2aaaab
	v_fma_f32 v161, v48, v161, 0.5
	v_fma_f32 v161, v48, v161, 1.0
	v_mul_f32_e64 v161, v161, -v48
	v_sub_f32_e32 v160, 1.0, v160
	v_cmp_nlt_f32_e64 s[6:7], s5, v48
	s_nop 1
	v_cndmask_b32_e64 v98, v161, v160, s[6:7]
	s_add_i32 s6, s4, 1
	s_add_i32 s26, s26, 1
	v_mov_b32_e32 v48, s6
	v_mov_b32_e32 v49, s26
	v_cndmask_b32_e32 v48, v48, v49, vcc
	v_add_u32_e32 v48, v48, v80
	v_mad_i64_i32 v[48:49], s[6:7], v48, s34, v[70:71]
	v_lshlrev_b64 v[52:53], 1, v[48:49]
	v_lshl_add_u64 v[48:49], v[72:73], 0, v[52:53]
	global_load_dwordx4 v[56:59], v[48:49], off nt
	v_lshl_add_u64 v[48:49], v[74:75], 0, v[52:53]
	v_lshl_add_u64 v[52:53], s[20:21], 0, v[52:53]
	global_load_dwordx4 v[48:51], v[48:49], off nt
	s_waitcnt vmcnt(1)
; __device__ __forceinline__ float sigmoidf_(float x) { return __builtin_amdgcn_rcpf(1.0f + __expf(-x)); }
; __device__ __forceinline__ void rg_unpack8(const u32x4 w, float* v) { v[0] = bflo(w.x); v[1] = bfhi(w.x); v[2] = bflo(w.y); v[3] = bfhi(w.y); v[4] = bflo(w.z); v[5] = bfhi(w.z); v[6] = bflo(w.w); v[7] = bfhi(w.w); }
; __device__ __forceinline__ void rg_ab(float ra, float ri, float x, float ba, float bx, float sp, float& a, float& b) {
;     const float r = sigmoidf_(ra + ba), ig = sigmoidf_(ri + bx); const float l2 = r * sp; a = exp2f(l2);
;     const float x2 = 1.3862943611198906f * l2;
;     const float om = x2 > -0.125f ? -x2 * (1.0f + x2 * (0.5f + x2 * (0.16666667f + x2 * (0.041666668f + x2 * 0.0083333338f)))) : 1.0f - __expf(x2);
; __device__ __forceinline__ void rg_scan1_phase(const bf16_t* RA0, const bf16_t* RI0, const bf16_t* RA1, const bf16_t* RI1, const bf16_t* XCV, const float* bap, const float* bxp, const float* lamp, float* CAR, int gtid, int ngt) {
;     ...
;         for (int i = 0; i < 32; ++i) { const size_t off = (size_t)(rbase + step * i) * DRNN + 8 * cg;
;             float ra[8], ri[8], xv[8]; rg_unpack8(*(const u32x4*)(RA + off), ra); rg_unpack8(*(const u32x4*)(RI + off), ri); rg_unpack8(*(const u32x4*)(XCV + off), xv);
; #pragma unroll
;             for (int e = 0; e < 8; ++e) { float a, bb; rg_ab(ra[e], ri[e], xv[e], ba[e], bx[e], sp[e], a, bb); p[e] *= a; sv[e] = a * sv[e] + bb; } }
	v_lshlrev_b32_e32 v60, 16, v56
	global_load_dwordx4 v[52:55], v[52:53], off nt
	v_add_f32_e32 v60, v0, v60
	v_mul_f32_e32 v60, 0xbfb8aa3b, v60
	v_exp_f32_e32 v60, v60
	s_nop 0
	v_add_f32_e32 v60, 1.0, v60
	v_rcp_f32_e32 v60, v60
	s_nop 0
	v_mul_f32_e32 v131, v88, v60
	v_mul_f32_e32 v60, 0x3fb17218, v131
	v_mul_f32_e32 v160, 0x3fb8aa3b, v60
	v_exp_f32_e32 v160, v160
	v_fmamk_f32 v161, v60, 0x3c088889, v202
	v_fmaak_f32 v161, v60, v161, 0x3e2aaaab
	v_fma_f32 v161, v60, v161, 0.5
	v_fma_f32 v161, v60, v161, 1.0
	v_mul_f32_e64 v161, v161, -v60
	v_sub_f32_e32 v160, 1.0, v160
	v_cmp_nlt_f32_e64 s[6:7], s5, v60
	s_nop 1
	v_cndmask_b32_e64 v110, v161, v160, s[6:7]
	v_and_b32_e32 v56, 0xffff0000, v56
	v_add_f32_e32 v56, v1, v56
	v_mul_f32_e32 v56, 0xbfb8aa3b, v56
	v_exp_f32_e32 v56, v56
	s_nop 0
	v_add_f32_e32 v56, 1.0, v56
	v_rcp_f32_e32 v56, v56
	s_nop 0
	v_mul_f32_e32 v133, v87, v56
	v_mul_f32_e32 v56, 0x3fb17218, v133
	v_mul_f32_e32 v160, 0x3fb8aa3b, v56
	v_exp_f32_e32 v160, v160
	v_fmamk_f32 v161, v56, 0x3c088889, v202
	v_fmaak_f32 v161, v56, v161, 0x3e2aaaab
	v_fma_f32 v161, v56, v161, 0.5
	v_fma_f32 v161, v56, v161, 1.0
	v_mul_f32_e64 v161, v161, -v56
	v_sub_f32_e32 v160, 1.0, v160
	v_cmp_nlt_f32_e64 s[6:7], s5, v56
	s_nop 1
	v_cndmask_b32_e64 v112, v161, v160, s[6:7]
	v_lshlrev_b32_e32 v56, 16, v57
	v_add_f32_e32 v56, v2, v56
	v_mul_f32_e32 v56, 0xbfb8aa3b, v56
	v_exp_f32_e32 v56, v56
	s_nop 0
	v_add_f32_e32 v56, 1.0, v56
	v_rcp_f32_e32 v56, v56
	s_nop 0
	v_mul_f32_e32 v135, v86, v56
	v_mul_f32_e32 v56, 0x3fb17218, v135
	v_mul_f32_e32 v160, 0x3fb8aa3b, v56
	v_exp_f32_e32 v160, v160
	v_fmamk_f32 v161, v56, 0x3c088889, v202
	v_fmaak_f32 v161, v56, v161, 0x3e2aaaab
	v_fma_f32 v161, v56, v161, 0.5
	v_fma_f32 v161, v56, v161, 1.0
	v_mul_f32_e64 v161, v161, -v56
	v_sub_f32_e32 v160, 1.0, v160
	v_cmp_nlt_f32_e64 s[6:7], s5, v56
	s_nop 1
	v_cndmask_b32_e64 v115, v161, v160, s[6:7]
	v_and_b32_e32 v56, 0xffff0000, v57
	v_add_f32_e32 v56, v3, v56
	v_mul_f32_e32 v56, 0xbfb8aa3b, v56
	v_exp_f32_e32 v56, v56
	s_nop 0
	v_add_f32_e32 v56, 1.0, v56
	v_rcp_f32_e32 v56, v56
	s_nop 0
	v_mul_f32_e32 v136, v85, v56
	v_mul_f32_e32 v56, 0x3fb17218, v136
	v_mul_f32_e32 v160, 0x3fb8aa3b, v56
	v_exp_f32_e32 v160, v160
	v_fmamk_f32 v161, v56, 0x3c088889, v202
	v_fmaak_f32 v161, v56, v161, 0x3e2aaaab
	v_fma_f32 v161, v56, v161, 0.5
	v_fma_f32 v161, v56, v161, 1.0
	v_mul_f32_e64 v161, v161, -v56
	v_sub_f32_e32 v160, 1.0, v160
	v_cmp_nlt_f32_e64 s[6:7], s5, v56
	s_nop 1
	v_cndmask_b32_e64 v121, v161, v160, s[6:7]
	v_lshlrev_b32_e32 v56, 16, v58
	v_add_f32_e32 v56, v8, v56
	v_mul_f32_e32 v56, 0xbfb8aa3b, v56
	v_exp_f32_e32 v56, v56
	s_nop 0
	v_add_f32_e32 v56, 1.0, v56
	v_rcp_f32_e32 v56, v56
	s_nop 0
	v_mul_f32_e32 v137, v84, v56
	v_mul_f32_e32 v56, 0x3fb17218, v137
	v_mul_f32_e32 v160, 0x3fb8aa3b, v56
	v_exp_f32_e32 v160, v160
	v_fmamk_f32 v161, v56, 0x3c088889, v202
	v_fmaak_f32 v161, v56, v161, 0x3e2aaaab
	v_fma_f32 v161, v56, v161, 0.5
	v_fma_f32 v161, v56, v161, 1.0
	v_mul_f32_e64 v161, v161, -v56
	v_sub_f32_e32 v160, 1.0, v160
	v_cmp_nlt_f32_e64 s[6:7], s5, v56
	s_nop 1
	v_cndmask_b32_e64 v127, v161, v160, s[6:7]
	v_and_b32_e32 v56, 0xffff0000, v58
	v_add_f32_e32 v56, v9, v56
	v_mul_f32_e32 v56, 0xbfb8aa3b, v56
	v_exp_f32_e32 v56, v56
	s_nop 0
	v_add_f32_e32 v56, 1.0, v56
	v_rcp_f32_e32 v56, v56
	s_nop 0
	v_mul_f32_e32 v138, v83, v56
	v_mul_f32_e32 v56, 0x3fb17218, v138
	v_mul_f32_e32 v160, 0x3fb8aa3b, v56
	v_exp_f32_e32 v160, v160
	v_fmamk_f32 v161, v56, 0x3c088889, v202
	v_fmaak_f32 v161, v56, v161, 0x3e2aaaab
	v_fma_f32 v161, v56, v161, 0.5
	v_fma_f32 v161, v56, v161, 1.0
	v_mul_f32_e64 v161, v161, -v56
	v_sub_f32_e32 v160, 1.0, v160
	v_cmp_nlt_f32_e64 s[6:7], s5, v56
	s_nop 1
	v_cndmask_b32_e64 v129, v161, v160, s[6:7]
	v_lshlrev_b32_e32 v56, 16, v59
	v_add_f32_e32 v56, v10, v56
	v_mul_f32_e32 v56, 0xbfb8aa3b, v56
	v_exp_f32_e32 v56, v56
	s_nop 0
	v_add_f32_e32 v56, 1.0, v56
	v_rcp_f32_e32 v56, v56
	s_nop 0
	v_mul_f32_e32 v139, v82, v56
	v_mul_f32_e32 v56, 0x3fb17218, v139
	v_mul_f32_e32 v160, 0x3fb8aa3b, v56
	v_exp_f32_e32 v160, v160
	v_fmamk_f32 v161, v56, 0x3c088889, v202
	v_fmaak_f32 v161, v56, v161, 0x3e2aaaab
	v_fma_f32 v161, v56, v161, 0.5
	v_fma_f32 v161, v56, v161, 1.0
	v_mul_f32_e64 v161, v161, -v56
	v_sub_f32_e32 v160, 1.0, v160
	v_cmp_nlt_f32_e64 s[6:7], s5, v56
	s_nop 1
	v_cndmask_b32_e64 v132, v161, v160, s[6:7]
	v_and_b32_e32 v56, 0xffff0000, v59
	v_add_f32_e32 v56, v11, v56
	v_mul_f32_e32 v56, 0xbfb8aa3b, v56
	v_exp_f32_e32 v56, v56
	s_nop 0
	v_add_f32_e32 v56, 1.0, v56
	v_rcp_f32_e32 v56, v56
	s_nop 0
	v_mul_f32_e32 v116, v81, v56
	v_mul_f32_e32 v56, 0x3fb17218, v116
	v_mul_f32_e32 v160, 0x3fb8aa3b, v56
	v_exp_f32_e32 v160, v160
	v_fmamk_f32 v161, v56, 0x3c088889, v202
	v_fmaak_f32 v161, v56, v161, 0x3e2aaaab
	v_fma_f32 v161, v56, v161, 0.5
	v_fma_f32 v161, v56, v161, 1.0
	v_mul_f32_e64 v161, v161, -v56
	v_sub_f32_e32 v160, 1.0, v160
	v_cmp_nlt_f32_e64 s[6:7], s5, v56
	s_nop 1
	v_cndmask_b32_e64 v114, v161, v160, s[6:7]
	s_add_i32 s26, s26, 1
	v_mov_b32_e32 v56, s4
	v_mov_b32_e32 v57, s26
	v_cndmask_b32_e32 v56, v56, v57, vcc
	v_add_u32_e32 v56, v56, v80
	v_mad_i64_i32 v[56:57], s[6:7], v56, s34, v[70:71]
	v_lshlrev_b64 v[60:61], 1, v[56:57]
	v_lshl_add_u64 v[56:57], v[72:73], 0, v[60:61]
	global_load_dwordx4 v[64:67], v[56:57], off nt
	v_lshl_add_u64 v[56:57], v[74:75], 0, v[60:61]
	v_lshl_add_u64 v[60:61], s[20:21], 0, v[60:61]
	global_load_dwordx4 v[56:59], v[56:57], off nt
	s_waitcnt vmcnt(1)
; __device__ __forceinline__ float sigmoidf_(float x) { return __builtin_amdgcn_rcpf(1.0f + __expf(-x)); }
; __device__ __forceinline__ void rg_unpack8(const u32x4 w, float* v) { v[0] = bflo(w.x); v[1] = bfhi(w.x); v[2] = bflo(w.y); v[3] = bfhi(w.y); v[4] = bflo(w.z); v[5] = bfhi(w.z); v[6] = bflo(w.w); v[7] = bfhi(w.w); }
; __device__ __forceinline__ void rg_ab(float ra, float ri, float x, float ba, float bx, float sp, float& a, float& b) {
;     const float r = sigmoidf_(ra + ba), ig = sigmoidf_(ri + bx); const float l2 = r * sp; a = exp2f(l2);
;     const float x2 = 1.3862943611198906f * l2;
;     const float om = x2 > -0.125f ? -x2 * (1.0f + x2 * (0.5f + x2 * (0.16666667f + x2 * (0.041666668f + x2 * 0.0083333338f)))) : 1.0f - __expf(x2);
; __device__ __forceinline__ void rg_scan1_phase(const bf16_t* RA0, const bf16_t* RI0, const bf16_t* RA1, const bf16_t* RI1, const bf16_t* XCV, const float* bap, const float* bxp, const float* lamp, float* CAR, int gtid, int ngt) {
;     ...
;         for (int i = 0; i < 32; ++i) { const size_t off = (size_t)(rbase + step * i) * DRNN + 8 * cg;
;             float ra[8], ri[8], xv[8]; rg_unpack8(*(const u32x4*)(RA + off), ra); rg_unpack8(*(const u32x4*)(RI + off), ri); rg_unpack8(*(const u32x4*)(XCV + off), xv);
; #pragma unroll
;             for (int e = 0; e < 8; ++e) { float a, bb; rg_ab(ra[e], ri[e], xv[e], ba[e], bx[e], sp[e], a, bb); p[e] *= a; sv[e] = a * sv[e] + bb; } }
	v_lshlrev_b32_e32 v126, 16, v64
	global_load_dwordx4 v[60:63], v[60:61], off nt
	v_add_f32_e32 v126, v0, v126
	v_mul_f32_e32 v126, 0xbfb8aa3b, v126
	v_exp_f32_e32 v126, v126
	s_nop 0
	v_add_f32_e32 v126, 1.0, v126
	v_rcp_f32_e32 v126, v126
	s_nop 0
	v_mul_f32_e32 v142, v88, v126
	v_mul_f32_e32 v128, 0x3fb17218, v142
	v_mul_f32_e32 v160, 0x3fb8aa3b, v128
	v_exp_f32_e32 v160, v160
	v_fmamk_f32 v161, v128, 0x3c088889, v202
	v_fmaak_f32 v161, v128, v161, 0x3e2aaaab
	v_fma_f32 v161, v128, v161, 0.5
	v_fma_f32 v161, v128, v161, 1.0
	v_mul_f32_e64 v161, v161, -v128
	v_sub_f32_e32 v160, 1.0, v160
	v_cmp_nlt_f32_e64 s[6:7], s5, v128
	s_nop 1
	v_cndmask_b32_e64 v126, v161, v160, s[6:7]
	v_and_b32_e32 v64, 0xffff0000, v64
	v_add_f32_e32 v64, v1, v64
	v_mul_f32_e32 v64, 0xbfb8aa3b, v64
	v_exp_f32_e32 v64, v64
	s_nop 0
	v_add_f32_e32 v64, 1.0, v64
	v_rcp_f32_e32 v64, v64
	s_nop 0
	v_mul_f32_e32 v144, v87, v64
	v_mul_f32_e32 v64, 0x3fb17218, v144
	v_mul_f32_e32 v160, 0x3fb8aa3b, v64
	v_exp_f32_e32 v160, v160
	v_fmamk_f32 v161, v64, 0x3c088889, v202
	v_fmaak_f32 v161, v64, v161, 0x3e2aaaab
	v_fma_f32 v161, v64, v161, 0.5
	v_fma_f32 v161, v64, v161, 1.0
	v_mul_f32_e64 v161, v161, -v64
	v_sub_f32_e32 v160, 1.0, v160
	v_cmp_nlt_f32_e64 s[6:7], s5, v64
	s_nop 1
	v_cndmask_b32_e64 v128, v161, v160, s[6:7]
	v_lshlrev_b32_e32 v64, 16, v65
	v_add_f32_e32 v64, v2, v64
	v_mul_f32_e32 v64, 0xbfb8aa3b, v64
	v_exp_f32_e32 v64, v64
	s_nop 0
	v_add_f32_e32 v64, 1.0, v64
	v_rcp_f32_e32 v64, v64
	s_nop 0
	v_mul_f32_e32 v145, v86, v64
	v_mul_f32_e32 v64, 0x3fb17218, v145
	v_mul_f32_e32 v160, 0x3fb8aa3b, v64
	v_exp_f32_e32 v160, v160
	v_fmamk_f32 v161, v64, 0x3c088889, v202
	v_fmaak_f32 v161, v64, v161, 0x3e2aaaab
	v_fma_f32 v161, v64, v161, 0.5
	v_fma_f32 v161, v64, v161, 1.0
	v_mul_f32_e64 v161, v161, -v64
	v_sub_f32_e32 v160, 1.0, v160
	v_cmp_nlt_f32_e64 s[6:7], s5, v64
	s_nop 1
	v_cndmask_b32_e64 v130, v161, v160, s[6:7]
	v_and_b32_e32 v64, 0xffff0000, v65
	v_add_f32_e32 v64, v3, v64
	v_mul_f32_e32 v64, 0xbfb8aa3b, v64
	v_exp_f32_e32 v64, v64
	s_nop 0
	v_add_f32_e32 v64, 1.0, v64
	v_rcp_f32_e32 v64, v64
	s_nop 0
	v_mul_f32_e32 v146, v85, v64
	v_mul_f32_e32 v64, 0x3fb17218, v146
	v_mul_f32_e32 v160, 0x3fb8aa3b, v64
	v_exp_f32_e32 v160, v160
	v_fmamk_f32 v161, v64, 0x3c088889, v202
	v_fmaak_f32 v161, v64, v161, 0x3e2aaaab
	v_fma_f32 v161, v64, v161, 0.5
	v_fma_f32 v161, v64, v161, 1.0
	v_mul_f32_e64 v161, v161, -v64
	v_sub_f32_e32 v160, 1.0, v160
	v_cmp_nlt_f32_e64 s[6:7], s5, v64
	s_nop 1
	v_cndmask_b32_e64 v134, v161, v160, s[6:7]
	v_lshlrev_b32_e32 v64, 16, v66
	v_add_f32_e32 v64, v8, v64
	v_mul_f32_e32 v64, 0xbfb8aa3b, v64
	v_exp_f32_e32 v64, v64
	s_nop 0
	v_add_f32_e32 v64, 1.0, v64
	v_rcp_f32_e32 v64, v64
	s_nop 0
	v_mul_f32_e32 v147, v84, v64
	v_mul_f32_e32 v64, 0x3fb17218, v147
	v_mul_f32_e32 v160, 0x3fb8aa3b, v64
	v_exp_f32_e32 v160, v160
	v_fmamk_f32 v161, v64, 0x3c088889, v202
	v_fmaak_f32 v161, v64, v161, 0x3e2aaaab
	v_fma_f32 v161, v64, v161, 0.5
	v_fma_f32 v161, v64, v161, 1.0
	v_mul_f32_e64 v161, v161, -v64
	v_sub_f32_e32 v160, 1.0, v160
	v_cmp_nlt_f32_e64 s[6:7], s5, v64
	s_nop 1
	v_cndmask_b32_e64 v140, v161, v160, s[6:7]
	v_and_b32_e32 v64, 0xffff0000, v66
	v_add_f32_e32 v64, v9, v64
	v_mul_f32_e32 v64, 0xbfb8aa3b, v64
	v_exp_f32_e32 v64, v64
	s_nop 0
	v_add_f32_e32 v64, 1.0, v64
	v_rcp_f32_e32 v64, v64
	s_nop 0
	v_mul_f32_e32 v148, v83, v64
	v_mul_f32_e32 v64, 0x3fb17218, v148
	v_mul_f32_e32 v160, 0x3fb8aa3b, v64
	v_exp_f32_e32 v160, v160
	v_fmamk_f32 v161, v64, 0x3c088889, v202
	v_fmaak_f32 v161, v64, v161, 0x3e2aaaab
	v_fma_f32 v161, v64, v161, 0.5
	v_fma_f32 v161, v64, v161, 1.0
	v_mul_f32_e64 v161, v161, -v64
	v_sub_f32_e32 v160, 1.0, v160
	v_cmp_nlt_f32_e64 s[6:7], s5, v64
	s_nop 1
	v_cndmask_b32_e64 v141, v161, v160, s[6:7]
	v_lshlrev_b32_e32 v64, 16, v67
	v_add_f32_e32 v64, v10, v64
	v_mul_f32_e32 v64, 0xbfb8aa3b, v64
	v_exp_f32_e32 v64, v64
	s_nop 0
	v_add_f32_e32 v64, 1.0, v64
	v_rcp_f32_e32 v64, v64
	s_nop 0
	v_mul_f32_e32 v149, v82, v64
	v_mul_f32_e32 v65, 0x3fb17218, v149
	v_mul_f32_e32 v160, 0x3fb8aa3b, v65
	v_exp_f32_e32 v160, v160
	v_fmamk_f32 v161, v65, 0x3c088889, v202
	v_fmaak_f32 v161, v65, v161, 0x3e2aaaab
	v_fma_f32 v161, v65, v161, 0.5
	v_fma_f32 v161, v65, v161, 1.0
	v_mul_f32_e64 v161, v161, -v65
	v_sub_f32_e32 v160, 1.0, v160
	v_cmp_nlt_f32_e64 s[6:7], s5, v65
	s_nop 1
	v_cndmask_b32_e64 v64, v161, v160, s[6:7]
	v_and_b32_e32 v65, 0xffff0000, v67
	v_add_f32_e32 v65, v11, v65
	v_mul_f32_e32 v65, 0xbfb8aa3b, v65
	v_exp_f32_e32 v65, v65
	s_nop 0
	v_add_f32_e32 v65, 1.0, v65
	v_rcp_f32_e32 v65, v65
	s_nop 0
	v_mul_f32_e32 v143, v81, v65
	v_mul_f32_e32 v66, 0x3fb17218, v143
	v_cmp_nlt_f32_e64 s[6:7], s5, v66
	s_and_saveexec_b64 s[28:29], s[6:7]
	s_xor_b64 s[6:7], exec, s[28:29]
	v_mul_f32_e32 v65, 0x3fb8aa3b, v66
	v_exp_f32_e32 v65, v65
	s_nop 0
	v_sub_f32_e32 v65, 1.0, v65
	s_andn2_saveexec_b64 s[6:7], s[6:7]
	s_cbranch_execz .LBB0_1013
	v_fmamk_f32 v65, v66, 0x3c088889, v202
	v_fmaak_f32 v65, v66, v65, 0x3e2aaaab
	v_fma_f32 v65, v66, v65, 0.5
	v_fma_f32 v65, v66, v65, 1.0
	v_mul_f32_e64 v65, v65, -v66
	s_branch .LBB0_1013
